# stack on v22: A-mixer loop-edge cleanup (SALU hoisted above step barriers, m0 save/restore dropped) + causal band-mask dispatch
# speedup vs baseline: 1.0006x; 1.0005x over previous
; #define WAIT_BAR(N) asm volatile("s_waitcnt vmcnt(%c0) lgkmcnt(0)\n\ts_barrier"::"n"(N):"memory")
;   #define RESC() do{ if(!FAST&&resc){ asm volatile("s_waitcnt lgkmcnt(0)":::"memory"); \
;       _Pragma("unroll") for(int d_=0;d_<ND;++d_) _Pragma("unroll") for(int r=0;r<16;++r)o[d_][r]*=wsf[crow(r,hi)]; } }while(0)
;   #define ROT() do{sl_prev=sl_cur;sl_cur=sl_next;sl_next=(sl_next==(NSLOT-1)*SLOTB)?0:sl_next+SLOTB;}while(0)
; template<int THRL,int MODE,int KVP,int DV,bool FAST> __device__ __forceinline__ void attn_unit(int b,int qb,const bf16*Qh,const bf16*__restrict__ Kh0,const bf16*__restrict__ Vh0,bf16*Oh,float sink_l2,const EpiArgs ea,char*shm){
;     ...
;   int t=1;
;     ...
;   if(MODE==0) for(;t+5<NT;t+=2){
;     STEP(pB0,pB1,pA0,pA1,t,true,true,true);     WAIT_BAR(1+NV); RESC(); ROT();
.LBB0_276:
	s_mov_b32 s4, s92
	s_mov_b32 s6, s89
	v_cvt_pk_bf16_f32 v154, v90, v91
	v_lshl_add_u32 v210, s7, 1, v235
	ds_read_b64_tr_b16 v[68:69], v210 offset:24576
	ds_read_b64_tr_b16 v[70:71], v210 offset:25088
	v_add_f32_e32 v67, v98, v99
	v_add_f32_e32 v67, v100, v67
	v_add_f32_e32 v67, v101, v67
	v_add_f32_e32 v67, v102, v67
	v_add_f32_e32 v67, v103, v67
	v_cvt_pk_bf16_f32 v174, v98, v99
	v_cvt_pk_bf16_f32 v175, v100, v101
	s_waitcnt lgkmcnt(9)
	v_mfma_f32_32x32x16_bf16 v[130:145], v[206:209], v[166:169], 0
	ds_read_b64_tr_b16 v[72:73], v210 offset:28672
	ds_read_b64_tr_b16 v[74:75], v210 offset:29184
	v_add_f32_e32 v67, v104, v67
	v_add_f32_e32 v67, v105, v67
	v_add_f32_e32 v67, v106, v67
	v_add_f32_e32 v67, v107, v67
	v_cvt_pk_bf16_f32 v176, v102, v103
	v_cvt_pk_bf16_f32 v177, v104, v105
	s_waitcnt lgkmcnt(10)
	v_mfma_f32_32x32x16_bf16 v[114:129], v[198:201], v[166:169], 0
	ds_read_b64_tr_b16 v[76:77], v210 offset:25600
	ds_read_b64_tr_b16 v[78:79], v210 offset:26112
	v_add_f32_e32 v67, v108, v67
	v_add_f32_e32 v67, v109, v67
	v_add_f32_e32 v67, v110, v67
	v_add_f32_e32 v67, v111, v67
	v_cvt_pk_bf16_f32 v170, v106, v107
	v_cvt_pk_bf16_f32 v171, v108, v109
	s_waitcnt lgkmcnt(11)
	v_mfma_f32_32x32x16_bf16 v[130:145], v[202:205], v[158:161], v[130:145]
	ds_read_b64_tr_b16 v[98:99], v210 offset:29696
	ds_read_b64_tr_b16 v[100:101], v210 offset:30208
	v_add_f32_e32 v67, v112, v67
	v_add_f32_e32 v67, v113, v67
	v_add_f32_e32 v67, v82, v67
	v_add_f32_e32 v67, v83, v67
	v_cvt_pk_bf16_f32 v172, v110, v111
	v_cvt_pk_bf16_f32 v173, v112, v113
	s_waitcnt lgkmcnt(12)
	v_mfma_f32_32x32x16_bf16 v[114:129], v[194:197], v[158:161], v[114:129]
	ds_read_b64_tr_b16 v[102:103], v210 offset:26624
	ds_read_b64_tr_b16 v[104:105], v210 offset:27136
	v_add_f32_e32 v67, v84, v67
	v_add_f32_e32 v67, v85, v67
	v_add_f32_e32 v67, v86, v67
	v_add_f32_e32 v67, v87, v67
	v_cvt_pk_bf16_f32 v162, v82, v83
	v_cvt_pk_bf16_f32 v163, v84, v85
	s_waitcnt lgkmcnt(13)
	v_mfma_f32_32x32x16_bf16 v[130:145], v[190:193], v[150:153], v[130:145]
	ds_read_b64_tr_b16 v[106:107], v210 offset:30720
	ds_read_b64_tr_b16 v[108:109], v210 offset:31232
	v_add_f32_e32 v67, v88, v67
	v_add_f32_e32 v67, v89, v67
	v_add_f32_e32 v67, v90, v67
	v_add_f32_e32 v67, v91, v67
	v_cvt_pk_bf16_f32 v164, v86, v87
	v_cvt_pk_bf16_f32 v165, v88, v89
	s_waitcnt lgkmcnt(14)
	v_mfma_f32_32x32x16_bf16 v[114:129], v[186:189], v[150:153], v[114:129]
	ds_read_b64_tr_b16 v[110:111], v210 offset:27648
	ds_read_b64_tr_b16 v[112:113], v210 offset:28160
	v_add_f32_e32 v67, v92, v67
	v_add_f32_e32 v67, v93, v67
	v_add_f32_e32 v67, v94, v67
	v_add_f32_e32 v67, v95, v67
	s_waitcnt lgkmcnt(14)
	v_mfma_f32_32x32x16_bf16 v[130:145], v[182:185], v[146:149], v[130:145]
	ds_read_b64_tr_b16 v[188:189], v210 offset:31744
	ds_read_b64_tr_b16 v[190:191], v210 offset:32256
	v_add_f32_e32 v67, v96, v67
	v_add_f32_e32 v67, v97, v67
	v_mfma_f32_32x32x16_bf16 v[114:129], v[178:181], v[146:149], v[114:129]
	s_add_u32 s8, s2, 0xfffe0000
	s_addc_u32 s9, s3, -1
	s_add_i32 s7, s89, s86
	s_mov_b32 m0, s7
	s_nop 0
	global_load_lds_dwordx4 v222, s[8:9]
	s_add_u32 s8, s0, 0xfffe0000
	s_addc_u32 s9, s1, -1
	s_lshl_b32 s7, s92, 1
	s_add_i32 s7, s7, s87
	s_mov_b32 m0, s7
	s_nop 0
	global_load_lds_dwordx4 v223, s[8:9]
	s_add_u32 s8, s0, 0xfffe0080
	s_addc_u32 s9, s1, -1
	s_addk_i32 s7, 0x2000
	s_mov_b32 m0, s7
	s_nop 0
	global_load_lds_dwordx4 v223, s[8:9]
	v_add_f32_e32 v186, v66, v67
	s_waitcnt lgkmcnt(14)
	v_mfma_f32_32x32x16_bf16 v[2:17], v[174:177], v[68:71], v[2:17]
	v_exp_f32_e32 v130, v130
	ds_read_b64_tr_b16 v[192:193], v210 offset:32768
	ds_read_b64_tr_b16 v[194:195], v210 offset:33280
	s_waitcnt lgkmcnt(14)
	v_mfma_f32_32x32x16_bf16 v[18:33], v[174:177], v[72:75], v[18:33]
	v_exp_f32_e32 v131, v131
	v_cvt_pk_bf16_f32 v155, v92, v93
	ds_read_b64_tr_b16 v[90:91], v210 offset:36864
	ds_read_b64_tr_b16 v[92:93], v210 offset:37376
	v_add_u32_e32 v66, s4, v237
	ds_read_b128 v[86:89], v66
	ds_read_b128 v[82:85], v66 offset:512
	s_waitcnt lgkmcnt(14)
	v_mfma_f32_32x32x16_bf16 v[2:17], v[170:173], v[76:79], v[2:17]
	v_exp_f32_e32 v132, v132
	v_cvt_pk_bf16_f32 v156, v94, v95
	ds_read_b64_tr_b16 v[196:197], v210 offset:33792
	ds_read_b64_tr_b16 v[198:199], v210 offset:34304
	ds_read_b128 v[182:185], v66 offset:2048
	ds_read_b128 v[78:81], v66 offset:2560
	v_mfma_f32_32x32x16_bf16 v[18:33], v[170:173], v[98:101], v[18:33]
	v_exp_f32_e32 v133, v133
	v_cvt_pk_bf16_f32 v157, v96, v97
	ds_read_b64_tr_b16 v[94:95], v210 offset:37888
	ds_read_b64_tr_b16 v[96:97], v210 offset:38400
	ds_read_b128 v[178:181], v66 offset:4096
	ds_read_b128 v[74:77], v66 offset:4608
	s_waitcnt lgkmcnt(14)
	v_mfma_f32_32x32x16_bf16 v[2:17], v[162:165], v[102:105], v[2:17]
	v_exp_f32_e32 v134, v134
	ds_read_b64_tr_b16 v[98:99], v210 offset:34816
	ds_read_b64_tr_b16 v[100:101], v210 offset:35328
	ds_read_b128 v[70:73], v66 offset:6144
	ds_read_b128 v[66:69], v66 offset:6656
	v_mfma_f32_32x32x16_bf16 v[18:33], v[162:165], v[106:109], v[18:33]
	v_exp_f32_e32 v135, v135
	ds_read_b64_tr_b16 v[102:103], v210 offset:38912
	ds_read_b64_tr_b16 v[104:105], v210 offset:39424
	v_mfma_f32_32x32x16_bf16 v[2:17], v[154:157], v[110:113], v[2:17]
	v_exp_f32_e32 v136, v136
	ds_read_b64_tr_b16 v[106:107], v210 offset:35840
	ds_read_b64_tr_b16 v[108:109], v210 offset:36352
	v_mfma_f32_32x32x16_bf16 v[18:33], v[154:157], v[188:191], v[18:33]
	v_exp_f32_e32 v137, v137
	ds_read_b64_tr_b16 v[110:111], v210 offset:39936
	ds_read_b64_tr_b16 v[112:113], v210 offset:40448
	s_waitcnt lgkmcnt(14)
	v_mfma_f32_32x32x16_bf16 v[34:49], v[174:177], v[192:195], v[34:49]
	v_exp_f32_e32 v138, v138
	v_exp_f32_e32 v114, v114
	v_exp_f32_e32 v115, v115
	v_mfma_f32_32x32x16_bf16 v[50:65], v[174:177], v[90:93], v[50:65]
	v_exp_f32_e32 v139, v139
	v_exp_f32_e32 v116, v116
	v_exp_f32_e32 v117, v117
	v_mfma_f32_32x32x16_bf16 v[34:49], v[170:173], v[196:199], v[34:49]
	v_exp_f32_e32 v140, v140
	v_exp_f32_e32 v118, v118
	v_exp_f32_e32 v119, v119
	s_waitcnt lgkmcnt(12)
	v_mfma_f32_32x32x16_bf16 v[50:65], v[170:173], v[94:97], v[50:65]
	v_exp_f32_e32 v141, v141
	v_exp_f32_e32 v120, v120
	v_exp_f32_e32 v121, v121
	s_waitcnt lgkmcnt(8)
	v_mfma_f32_32x32x16_bf16 v[34:49], v[162:165], v[98:101], v[34:49]
	v_exp_f32_e32 v142, v142
	v_exp_f32_e32 v122, v122
	v_exp_f32_e32 v123, v123
	s_waitcnt lgkmcnt(4)
	v_mfma_f32_32x32x16_bf16 v[50:65], v[162:165], v[102:105], v[50:65]
	v_exp_f32_e32 v143, v143
	v_exp_f32_e32 v124, v124
	v_exp_f32_e32 v125, v125
	s_waitcnt lgkmcnt(2)
	v_mfma_f32_32x32x16_bf16 v[34:49], v[154:157], v[106:109], v[34:49]
	v_exp_f32_e32 v144, v144
	v_exp_f32_e32 v126, v126
	v_exp_f32_e32 v127, v127
	s_waitcnt lgkmcnt(0)
	v_mfma_f32_32x32x16_bf16 v[50:65], v[154:157], v[110:113], v[50:65]
	v_exp_f32_e32 v145, v145
	v_exp_f32_e32 v128, v128
	v_exp_f32_e32 v129, v129
	s_add_i32 s7, s92, 0x2000
	s_cmpk_lg_i32 s92, 0x4000
	s_cselect_b32 s89, s7, 0
	s_waitcnt vmcnt(3) lgkmcnt(0)
	s_barrier
; #define WAIT_BAR(N) asm volatile("s_waitcnt vmcnt(%c0) lgkmcnt(0)\n\ts_barrier"::"n"(N):"memory")
;   #define RESC() do{ if(!FAST&&resc){ asm volatile("s_waitcnt lgkmcnt(0)":::"memory"); \
;       _Pragma("unroll") for(int d_=0;d_<ND;++d_) _Pragma("unroll") for(int r=0;r<16;++r)o[d_][r]*=wsf[crow(r,hi)]; } }while(0)
;   #define ROT() do{sl_prev=sl_cur;sl_cur=sl_next;sl_next=(sl_next==(NSLOT-1)*SLOTB)?0:sl_next+SLOTB;}while(0)
; template<int THRL,int MODE,int KVP,int DV,bool FAST> __device__ __forceinline__ void attn_unit(int b,int qb,const bf16*Qh,const bf16*__restrict__ Kh0,const bf16*__restrict__ Vh0,bf16*Oh,float sink_l2,const EpiArgs ea,char*shm){
;     ...
;   int t=1;
;     ...
;   if(MODE==0) for(;t+5<NT;t+=2){
;     STEP(pB0,pB1,pA0,pA1,t,true,true,true);     WAIT_BAR(1+NV); RESC(); ROT();
;     STEP(pA0,pA1,pB0,pB1,t+1,true,true,true);   WAIT_BAR(1+NV); RESC(); ROT();
;   }
	v_lshl_add_u32 v210, s6, 1, v235
	ds_read_b64_tr_b16 v[188:189], v210 offset:24576
	ds_read_b64_tr_b16 v[190:191], v210 offset:25088
	v_mfma_f32_32x32x16_bf16 v[98:113], v[86:89], v[166:169], 0
	v_add_f32_e32 v90, v130, v131
	v_add_f32_e32 v90, v132, v90
	v_add_f32_e32 v90, v133, v90
	v_add_f32_e32 v90, v134, v90
	v_add_f32_e32 v90, v135, v90
	v_cvt_pk_bf16_f32 v174, v130, v131
	v_cvt_pk_bf16_f32 v175, v132, v133
	ds_read_b64_tr_b16 v[130:131], v210 offset:28672
	ds_read_b64_tr_b16 v[132:133], v210 offset:29184
	v_add_f32_e32 v86, v136, v90
	v_add_f32_e32 v86, v137, v86
	v_add_f32_e32 v86, v138, v86
	v_add_f32_e32 v154, v139, v86
	v_mfma_f32_32x32x16_bf16 v[82:97], v[82:85], v[166:169], 0
	v_cvt_pk_bf16_f32 v176, v134, v135
	v_cvt_pk_bf16_f32 v177, v136, v137
	ds_read_b64_tr_b16 v[134:135], v210 offset:25600
	ds_read_b64_tr_b16 v[136:137], v210 offset:26112
	v_mfma_f32_32x32x16_bf16 v[98:113], v[182:185], v[158:161], v[98:113]
	v_add_f32_e32 v154, v140, v154
	v_add_f32_e32 v154, v141, v154
	v_add_f32_e32 v154, v142, v154
	v_add_f32_e32 v154, v143, v154
	v_cvt_pk_bf16_f32 v170, v138, v139
	v_cvt_pk_bf16_f32 v171, v140, v141
	ds_read_b64_tr_b16 v[138:139], v210 offset:29696
	ds_read_b64_tr_b16 v[140:141], v210 offset:30208
	v_mfma_f32_32x32x16_bf16 v[82:97], v[78:81], v[158:161], v[82:97]
	v_add_f32_e32 v78, v144, v154
	v_add_f32_e32 v78, v145, v78
	v_add_f32_e32 v78, v114, v78
	v_add_f32_e32 v154, v115, v78
	v_cvt_pk_bf16_f32 v172, v142, v143
	v_cvt_pk_bf16_f32 v173, v144, v145
	ds_read_b64_tr_b16 v[78:79], v210 offset:26624
	ds_read_b64_tr_b16 v[80:81], v210 offset:27136
	v_mfma_f32_32x32x16_bf16 v[98:113], v[178:181], v[150:153], v[98:113]
	v_add_f32_e32 v142, v116, v154
	v_add_f32_e32 v142, v117, v142
	v_add_f32_e32 v142, v118, v142
	v_add_f32_e32 v142, v119, v142
	v_cvt_pk_bf16_f32 v162, v114, v115
	v_cvt_pk_bf16_f32 v163, v116, v117
	ds_read_b64_tr_b16 v[114:115], v210 offset:30720
	ds_read_b64_tr_b16 v[116:117], v210 offset:31232
	v_mfma_f32_32x32x16_bf16 v[82:97], v[74:77], v[150:153], v[82:97]
	v_add_f32_e32 v74, v120, v142
	v_add_f32_e32 v74, v121, v74
	v_add_f32_e32 v74, v122, v74
	v_add_f32_e32 v142, v123, v74
	v_cvt_pk_bf16_f32 v164, v118, v119
	v_cvt_pk_bf16_f32 v165, v120, v121
	ds_read_b64_tr_b16 v[74:75], v210 offset:27648
	ds_read_b64_tr_b16 v[76:77], v210 offset:28160
	v_mfma_f32_32x32x16_bf16 v[98:113], v[70:73], v[146:149], v[98:113]
	v_add_f32_e32 v70, v124, v142
	v_add_f32_e32 v70, v125, v70
	v_add_f32_e32 v70, v126, v70
	v_add_f32_e32 v118, v127, v70
	ds_read_b64_tr_b16 v[70:71], v210 offset:31744
	ds_read_b64_tr_b16 v[72:73], v210 offset:32256
	v_mfma_f32_32x32x16_bf16 v[82:97], v[66:69], v[146:149], v[82:97]
	v_add_f32_e32 v66, v128, v118
	v_add_f32_e32 v66, v129, v66
	s_add_i32 s6, s92, s86
	s_mov_b32 m0, s6
	s_nop 0
	global_load_lds_dwordx4 v222, s[2:3]
	s_lshl_b32 s6, s89, 1
	s_add_i32 s76, s76, 2
	s_add_i32 s8, s6, s87
	s_mov_b32 m0, s8
	s_nop 0
	global_load_lds_dwordx4 v223, s[0:1]
	s_add_u32 s6, s0, 0x80
	s_addc_u32 s7, s1, 0
	s_addk_i32 s8, 0x2000
	s_mov_b32 m0, s8
	s_nop 0
	global_load_lds_dwordx4 v223, s[6:7]
	v_add_f32_e32 v66, v186, v66
	s_waitcnt lgkmcnt(14)
	v_mfma_f32_32x32x16_bf16 v[2:17], v[174:177], v[188:191], v[2:17]
	v_exp_f32_e32 v98, v98
	v_cvt_pk_bf16_f32 v154, v122, v123
	ds_read_b64_tr_b16 v[118:119], v210 offset:32768
	ds_read_b64_tr_b16 v[120:121], v210 offset:33280
	s_waitcnt lgkmcnt(14)
	v_mfma_f32_32x32x16_bf16 v[18:33], v[174:177], v[130:133], v[18:33]
	v_exp_f32_e32 v99, v99
	v_cvt_pk_bf16_f32 v155, v124, v125
	ds_read_b64_tr_b16 v[122:123], v210 offset:36864
	ds_read_b64_tr_b16 v[124:125], v210 offset:37376
	v_add_u32_e32 v67, s89, v237
	ds_read_b128 v[206:209], v67
	ds_read_b128 v[198:201], v67 offset:512
	s_waitcnt lgkmcnt(14)
	v_mfma_f32_32x32x16_bf16 v[2:17], v[170:173], v[134:137], v[2:17]
	v_exp_f32_e32 v100, v100
	v_cvt_pk_bf16_f32 v156, v126, v127
	ds_read_b64_tr_b16 v[130:131], v210 offset:33792
	ds_read_b64_tr_b16 v[132:133], v210 offset:34304
	ds_read_b128 v[202:205], v67 offset:2048
	ds_read_b128 v[194:197], v67 offset:2560
	v_mfma_f32_32x32x16_bf16 v[18:33], v[170:173], v[138:141], v[18:33]
	v_exp_f32_e32 v101, v101
	v_cvt_pk_bf16_f32 v157, v128, v129
	ds_read_b64_tr_b16 v[126:127], v210 offset:37888
	ds_read_b64_tr_b16 v[128:129], v210 offset:38400
	ds_read_b128 v[190:193], v67 offset:4096
	ds_read_b128 v[186:189], v67 offset:4608
	s_waitcnt lgkmcnt(14)
	v_mfma_f32_32x32x16_bf16 v[2:17], v[162:165], v[78:81], v[2:17]
	v_exp_f32_e32 v102, v102
	ds_read_b64_tr_b16 v[78:79], v210 offset:34816
	ds_read_b64_tr_b16 v[80:81], v210 offset:35328
	ds_read_b128 v[182:185], v67 offset:6144
	ds_read_b128 v[178:181], v67 offset:6656
	v_mfma_f32_32x32x16_bf16 v[18:33], v[162:165], v[114:117], v[18:33]
	v_exp_f32_e32 v103, v103
	ds_read_b64_tr_b16 v[114:115], v210 offset:38912
	ds_read_b64_tr_b16 v[116:117], v210 offset:39424
	v_mfma_f32_32x32x16_bf16 v[2:17], v[154:157], v[74:77], v[2:17]
	v_exp_f32_e32 v104, v104
	ds_read_b64_tr_b16 v[74:75], v210 offset:35840
	ds_read_b64_tr_b16 v[76:77], v210 offset:36352
	v_mfma_f32_32x32x16_bf16 v[18:33], v[154:157], v[70:73], v[18:33]
	v_exp_f32_e32 v105, v105
	ds_read_b64_tr_b16 v[68:69], v210 offset:39936
	ds_read_b64_tr_b16 v[70:71], v210 offset:40448
	s_waitcnt lgkmcnt(14)
	v_mfma_f32_32x32x16_bf16 v[34:49], v[174:177], v[118:121], v[34:49]
	v_exp_f32_e32 v106, v106
	v_exp_f32_e32 v82, v82
	v_exp_f32_e32 v83, v83
	v_mfma_f32_32x32x16_bf16 v[50:65], v[174:177], v[122:125], v[50:65]
	v_exp_f32_e32 v107, v107
	v_exp_f32_e32 v84, v84
	v_exp_f32_e32 v85, v85
	v_mfma_f32_32x32x16_bf16 v[34:49], v[170:173], v[130:133], v[34:49]
	v_exp_f32_e32 v108, v108
	v_exp_f32_e32 v86, v86
	v_exp_f32_e32 v87, v87
	s_waitcnt lgkmcnt(12)
	v_mfma_f32_32x32x16_bf16 v[50:65], v[170:173], v[126:129], v[50:65]
	v_exp_f32_e32 v109, v109
	v_exp_f32_e32 v88, v88
	v_exp_f32_e32 v89, v89
	s_waitcnt lgkmcnt(8)
	v_mfma_f32_32x32x16_bf16 v[34:49], v[162:165], v[78:81], v[34:49]
	v_exp_f32_e32 v110, v110
	v_exp_f32_e32 v90, v90
	v_exp_f32_e32 v91, v91
	s_waitcnt lgkmcnt(4)
	v_mfma_f32_32x32x16_bf16 v[50:65], v[162:165], v[114:117], v[50:65]
	v_exp_f32_e32 v111, v111
	v_exp_f32_e32 v92, v92
	v_exp_f32_e32 v93, v93
	s_waitcnt lgkmcnt(2)
	v_mfma_f32_32x32x16_bf16 v[34:49], v[154:157], v[74:77], v[34:49]
	v_exp_f32_e32 v112, v112
	v_exp_f32_e32 v94, v94
	v_exp_f32_e32 v95, v95
	s_waitcnt lgkmcnt(0)
	v_mfma_f32_32x32x16_bf16 v[50:65], v[154:157], v[68:71], v[50:65]
	v_exp_f32_e32 v113, v113
	v_exp_f32_e32 v96, v96
	v_exp_f32_e32 v97, v97
	s_add_i32 s6, s89, 0x2000
	s_cmpk_lg_i32 s89, 0x4000
	s_cselect_b32 s92, s6, 0
	s_add_u32 s0, s0, 0x40000
	s_addc_u32 s1, s1, 0
	s_add_u32 s2, s2, 0x40000
	s_addc_u32 s3, s3, 0
	s_cmp_ge_i32 s76, s5
	s_mov_b32 s7, s4
	s_waitcnt vmcnt(3) lgkmcnt(0)
	s_barrier
	s_cbranch_scc0 .LBB0_276
	s_branch .LBB0_278
